# mix-phase work queue: the next pop's atomic is issued when an attention/FFT item starts (index prefetched into a spare VGPR lane)
# speedup vs baseline: 1.0104x; 1.0008x over previous
.LBB0_138:
	s_andn2_b64 vcc, exec, s[0:1]
	s_cbranch_vccnz .LBB0_225
	s_and_b64 s[0:1], s[10:11], exec
	s_movk_i32 s0, 0xad
	s_cselect_b32 s9, 8, 0
	s_cselect_b32 s51, s0, 0xa0
	s_lshl_b64 s[0:1], s[94:95], 2
	v_readlane_b32 s2, v252, 34
	s_add_u32 s2, s2, s0
	v_readlane_b32 s0, v252, 35
	v_readlane_b32 s4, v255, 13
	s_addc_u32 s3, s0, s1
	v_cndmask_b32_e64 v0, 0, 1, s[10:11]
	v_readlane_b32 s5, v255, 14
	v_writelane_b32 v255, s2, 19
	s_lshl_b32 s10, s4, 9
	s_lshl_b32 s0, s4, 7
	v_readlane_b32 s76, v253, 40
	v_writelane_b32 v255, s3, 20
	s_mul_i32 s3, s4, 0xf800
	s_ashr_i32 s11, s10, 31
	s_ashr_i32 s1, s0, 31
	v_readlane_b32 s86, v253, 50
	s_mul_hi_i32 s2, s4, 0xf800
	v_readlane_b32 s87, v253, 51
	s_add_u32 s12, s86, s3
	s_addc_u32 s13, s87, s2
	v_writelane_b32 v255, s12, 21
	s_mov_b32 s2, s10
	v_readfirstlane_b32 s55, v0
	v_writelane_b32 v255, s13, 22
	v_writelane_b32 v255, s2, 23
	v_cvt_f32_i32_e32 v0, s4
	v_readlane_b32 s90, v253, 54
	v_writelane_b32 v255, s3, 24
	s_lshl_b64 s[2:3], s[10:11], 2
	v_readlane_b32 s77, v253, 41
	v_readlane_b32 s78, v253, 42
	v_readlane_b32 s79, v253, 43
	v_readlane_b32 s80, v253, 44
	v_readlane_b32 s81, v253, 45
	v_readlane_b32 s82, v253, 46
	v_readlane_b32 s83, v253, 47
	v_readlane_b32 s84, v253, 48
	v_readlane_b32 s85, v253, 49
	v_readlane_b32 s88, v253, 52
	v_readlane_b32 s89, v253, 53
	v_readlane_b32 s91, v253, 55
	s_add_u32 s52, s90, s2
	s_addc_u32 s53, s91, s3
	v_readlane_b32 s76, v254, 34
	v_readlane_b32 s77, v254, 35
	s_add_u32 s36, s76, s2
	v_mul_f32_e32 v0, 0xbe99999a, v0
	s_addc_u32 s37, s77, s3
	s_lshl_b64 s[2:3], s[4:5], 2
	v_readlane_b32 s4, v251, 57
	v_mul_f32_e32 v0, 0x3fb8aa3b, v0
	v_readlane_b32 s5, v251, 58
	s_add_u32 s76, s4, s2
	v_exp_f32_e32 v0, v0
	v_readlane_b32 s90, v254, 48
	s_addc_u32 s77, s5, s3
	s_lshl_b64 s[0:1], s[0:1], 2
	s_add_u32 s66, s90, s0
	s_getreg_b32 s0, hwreg(HW_REG_XCC_ID, 0, 4)
	v_writelane_b32 v255, s0, 25
	s_waitcnt lgkmcnt(0)
	v_mov_b32_e32 v1, 0xbf4ccccd
	v_readlane_b32 s80, v254, 38
	v_writelane_b32 v255, s94, 26
	v_fmamk_f32 v0, v0, 0x3f19999a, v1
	v_readlane_b32 s78, v254, 36
	v_readlane_b32 s79, v254, 37
	v_readlane_b32 s91, v254, 49
	s_mov_b32 s80, s9
	v_writelane_b32 v255, s95, 27
	s_mov_b32 s50, 0
	v_add_f32_e32 v162, 1.0, v0
	s_movk_i32 s30, 0x1000
	s_mov_b32 s92, 0xf800000
	s_mov_b32 s93, 0x1513d000
	s_movk_i32 s79, 0x100
	s_movk_i32 s78, 0x200
	s_addc_u32 s67, s91, s1
	s_movk_i32 s2, 0xff
	v_writelane_b32 v255, s80, 28
	v_readlane_b32 s81, v254, 39
	v_readlane_b32 s82, v254, 40
	v_readlane_b32 s83, v254, 41
	v_readlane_b32 s84, v254, 42
	v_readlane_b32 s85, v254, 43
	v_readlane_b32 s86, v254, 44
	v_readlane_b32 s87, v254, 45
	v_readlane_b32 s88, v254, 46
	v_readlane_b32 s89, v254, 47
	v_writelane_b32 v255, 0, 41
	s_branch .LBB0_142

.LBB0_151:
	s_waitcnt vmcnt(0) lgkmcnt(0)
	s_barrier
	s_and_saveexec_b64 s[0:1], s[60:61]
	s_cbranch_execz .LBB0_155
	v_readlane_b32 s2, v255, 41
	s_cmp_eq_u32 s2, 0
	s_cbranch_scc1 .Lqpf_normal
	v_readlane_b32 s2, v255, 40
	v_mov_b32_e32 v0, 0
	v_writelane_b32 v255, 0, 41
	s_branch .Lqpf_have
.Lqpf_normal:
	s_mov_b64 s[4:5], exec
	v_mbcnt_lo_u32_b32 v0, s4, 0
	v_mbcnt_hi_u32_b32 v0, s5, v0
	v_cmp_eq_u32_e32 vcc, 0, v0
	s_and_saveexec_b64 s[2:3], vcc
	s_cbranch_execz .LBB0_154
	s_bcnt1_i32_b64 s4, s[4:5]
	v_mov_b32_e32 v1, s4
	global_atomic_add v1, v193, v1, s[12:13] sc0

.Lqpf_have:
	v_mov_b32_e32 v1, s6
	s_nop 0
	v_add_u32_e32 v0, s2, v0
	ds_write_b32 v1, v0
.LBB0_155:
	s_or_b64 exec, exec, s[0:1]
	v_mov_b32_e32 v0, s6
	s_waitcnt lgkmcnt(0)
	s_barrier
	ds_read_b32 v0, v0
	s_mov_b64 s[0:1], -1
	s_waitcnt lgkmcnt(0)
	v_cmp_le_i32_e32 vcc, s51, v0
	v_readfirstlane_b32 s41, v0
	s_cbranch_vccnz .LBB0_150
	v_readfirstlane_b32 s98, v224
	s_cmp_lg_u32 s98, 0
	s_cbranch_scc1 .Lqpf_skip
	s_cmp_ge_i32 s41, 128
	s_cbranch_scc1 .Lqpf_skip
	s_mov_b64 s[98:99], exec
	s_mov_b32 exec_lo, 0
	s_mov_b32 exec_hi, 0x100
	global_atomic_add v255, v193, v226, s[12:13] sc0
	s_mov_b64 exec, s[98:99]
	s_mov_b32 s98, 1
	s_nop 1
	v_writelane_b32 v255, s98, 41
.Lqpf_skip:
	s_cmp_gt_i32 s41, 63
	s_cbranch_scc0 .LBB0_206
	s_cmpk_gt_u32 s41, 0x7f
	s_cbranch_scc0 .LBB0_203
	s_add_i32 s2, s41, 0xffffff80
	s_cmp_ge_i32 s2, s55
	s_cbranch_scc0 .LBB0_194
	s_sub_i32 s31, s2, s55
	s_cmp_ge_i32 s31, s80
	s_cbranch_scc0 .LBB0_180
	v_readlane_b32 s1, v255, 10
	s_sub_i32 s0, s31, s80
	s_mul_i32 s1, s54, s1
	s_add_i32 s0, s0, s1
	s_lshl_b32 s48, s0, 5
	s_cmpk_gt_u32 s0, 0xff
	s_mov_b64 s[0:1], -1
	s_cbranch_scc0 .LBB0_173
	v_mov_b32_e32 v139, v224
	s_movk_i32 s0, 0xf80
	s_nop 0
	v_cmp_gt_i32_e32 vcc, s0, v139
	s_and_saveexec_b64 s[0:1], vcc
	s_movk_i32 s9, 0xd7f
	s_cbranch_execz .LBB0_166
	s_and_b32 s47, s48, 0xe0
	s_and_b32 s46, s48, 0xffffff00
	s_add_i32 s47, s47, -15
	v_lshlrev_b32_e32 v4, 2, v139
	s_mov_b64 s[2:3], 0
	v_mov_b32_e32 v5, v139
	s_branch .LBB0_164
